# stack6 + attention output-gate rows requested one step earlier (into the dead Q-fragment registers)
# baseline (speedup 1.0000x reference)
; #define GAS __attribute__((address_space(1)))
; template <int THRL, bool FIXM> __device__ __forceinline__ bool attn_unit(const h16* Qrows, const h16* __restrict__ Kh, const h16* __restrict__ Vh, const int NT, h16* Yrows, const h16* BZrows, char* shm, const int tid, const float mfix, ...
;     ...
;   h16x8 zg[4];
;   { const h16* Zw0 = BZrows + (long)(wid * QBLK) * ZP;
; #pragma unroll
;     for (int i = 0; i < 4; ++i) zg[i] = *(const GAS h16x8*)(Zw0 + (long)(i * 8 + (lane >> 3)) * ZP + (lane & 7) * 8); }
.LBB0_124:
	s_lshl_b64 vcc, s[24:25], 1
	s_add_u32 vcc_lo, s82, vcc_lo
	s_addc_u32 vcc_hi, s81, vcc_hi
	v_and_b32_e32 v116, 56, v131
	v_mov_b32_e32 v117, v1
	v_lshlrev_b32_e32 v116, 1, v116
	v_lshl_add_u64 v[114:115], vcc, 0, v[116:117]
	v_and_b32_e32 v116, 0xe00, v230
	v_lshlrev_b32_e32 v116, 1, v116
	v_lshl_add_u64 v[114:115], v[114:115], 0, v[116:117]
	s_movk_i32 vcc_lo, 0x2000
	s_mov_b32 vcc_hi, 0
	global_load_dwordx4 v[126:129], v[114:115], off
	v_lshl_add_u64 v[116:117], v[114:115], 0, vcc
	s_movk_i32 vcc_lo, 0x4000
	global_load_dwordx4 v[122:125], v[116:117], off
	v_lshl_add_u64 v[116:117], v[114:115], 0, vcc
	s_movk_i32 vcc_lo, 0x6000
	global_load_dwordx4 v[118:121], v[116:117], off
	v_lshl_add_u64 v[114:115], v[114:115], 0, vcc
	s_nop 0
	global_load_dwordx4 v[114:117], v[114:115], off
	s_and_b32 s12, s29, 0x3fffffc0
	s_lshl_b32 s12, s12, 2
	s_add_i32 s14, s41, s12
	v_add_u32_e32 v0, s51, v233
	ds_read_b64_tr_b16 v[52:53], v0 offset:24576
	ds_read_b64_tr_b16 v[54:55], v0 offset:25088
	v_add_f32_e32 v51, v82, v83
	v_add_f32_e32 v51, v84, v51
	v_add_f32_e32 v51, v85, v51
	v_add_f32_e32 v51, v86, v51
	v_add_f32_e32 v51, v87, v51
	v_cvt_pk_f16_f32 v160, v82, v83
	v_cvt_pk_f16_f32 v161, v84, v85
	s_waitcnt lgkmcnt(9)
	v_mfma_f32_32x32x16_f16 v[98:113], v[192:195], v[144:147], v[2:17]
	ds_read_b64_tr_b16 v[56:57], v0 offset:28672
	ds_read_b64_tr_b16 v[58:59], v0 offset:29184
	s_waitcnt lgkmcnt(10)
	v_mfma_f32_32x32x16_f16 v[2:17], v[188:191], v[144:147], v[2:17]
	v_add_f32_e32 v51, v88, v51
	v_add_f32_e32 v51, v89, v51
	v_add_f32_e32 v51, v90, v51
	v_add_f32_e32 v51, v91, v51
	v_cvt_pk_f16_f32 v162, v86, v87
	v_cvt_pk_f16_f32 v163, v88, v89
	ds_read_b64_tr_b16 v[60:61], v0 offset:25600
	ds_read_b64_tr_b16 v[62:63], v0 offset:26112
	v_add_f32_e32 v51, v92, v51
	v_add_f32_e32 v51, v93, v51
	v_add_f32_e32 v51, v94, v51
	v_add_f32_e32 v51, v95, v51
	v_cvt_pk_f16_f32 v156, v90, v91
	v_cvt_pk_f16_f32 v157, v92, v93
	s_waitcnt lgkmcnt(11)
	v_mfma_f32_32x32x16_f16 v[98:113], v[184:187], v[140:143], v[98:113]
	ds_read_b64_tr_b16 v[82:83], v0 offset:29696
	ds_read_b64_tr_b16 v[84:85], v0 offset:30208
	s_waitcnt lgkmcnt(12)
	v_mfma_f32_32x32x16_f16 v[2:17], v[180:183], v[140:143], v[2:17]
	v_add_f32_e32 v51, v96, v51
	v_add_f32_e32 v51, v97, v51
	v_add_f32_e32 v51, v66, v51
	v_add_f32_e32 v51, v67, v51
	v_cvt_pk_f16_f32 v158, v94, v95
	v_cvt_pk_f16_f32 v159, v96, v97
	ds_read_b64_tr_b16 v[86:87], v0 offset:26624
	ds_read_b64_tr_b16 v[88:89], v0 offset:27136
	v_add_f32_e32 v51, v68, v51
	v_add_f32_e32 v51, v69, v51
	v_add_f32_e32 v51, v70, v51
	v_add_f32_e32 v51, v71, v51
	v_cvt_pk_f16_f32 v152, v66, v67
	v_cvt_pk_f16_f32 v153, v68, v69
	s_waitcnt lgkmcnt(13)
	v_mfma_f32_32x32x16_f16 v[98:113], v[176:179], v[136:139], v[98:113]
	ds_read_b64_tr_b16 v[64:65], v0 offset:30720
	ds_read_b64_tr_b16 v[66:67], v0 offset:31232
	s_waitcnt lgkmcnt(14)
	v_mfma_f32_32x32x16_f16 v[2:17], v[172:175], v[136:139], v[2:17]
	v_add_f32_e32 v51, v72, v51
	v_add_f32_e32 v51, v73, v51
	v_add_f32_e32 v51, v74, v51
	v_add_f32_e32 v51, v75, v51
	v_cvt_pk_f16_f32 v154, v70, v71
	v_cvt_pk_f16_f32 v155, v72, v73
	ds_read_b64_tr_b16 v[68:69], v0 offset:27648
	ds_read_b64_tr_b16 v[70:71], v0 offset:28160
	v_add_f32_e32 v51, v76, v51
	v_add_f32_e32 v51, v77, v51
	v_add_f32_e32 v51, v78, v51
	v_add_f32_e32 v51, v79, v51
	v_cvt_pk_f16_f32 v148, v74, v75
	v_cvt_pk_f16_f32 v149, v76, v77
	s_waitcnt lgkmcnt(14)
	v_mfma_f32_32x32x16_f16 v[98:113], v[168:171], v[132:135], v[98:113]
	ds_read_b64_tr_b16 v[72:73], v0 offset:31744
	ds_read_b64_tr_b16 v[74:75], v0 offset:32256
	v_mfma_f32_32x32x16_f16 v[2:17], v[164:167], v[132:135], v[2:17]
	v_add_f32_e32 v0, v80, v51
	v_add_f32_e32 v0, v81, v0
	v_add_f32_e32 v0, 0, v0
	v_cvt_pk_f16_f32 v150, v78, v79
	v_cvt_pk_f16_f32 v151, v80, v81
	s_waitcnt lgkmcnt(14)
	v_mfma_f32_32x32x16_f16 v[18:33], v[160:163], v[52:55], v[18:33]
	s_nop 1
	v_exp_f32_e32 v98, v98
	v_exp_f32_e32 v99, v99
	v_exp_f32_e32 v100, v100
	v_exp_f32_e32 v101, v101
	s_waitcnt lgkmcnt(12)
	v_mfma_f32_32x32x16_f16 v[34:49], v[160:163], v[56:59], v[34:49]
	v_exp_f32_e32 v102, v102
	v_exp_f32_e32 v103, v103
	v_exp_f32_e32 v104, v104
	v_exp_f32_e32 v105, v105
	s_waitcnt lgkmcnt(10)
	v_mfma_f32_32x32x16_f16 v[18:33], v[156:159], v[60:63], v[18:33]
	v_exp_f32_e32 v106, v106
	v_exp_f32_e32 v107, v107
	v_exp_f32_e32 v108, v108
	v_exp_f32_e32 v109, v109
	s_waitcnt lgkmcnt(8)
	v_mfma_f32_32x32x16_f16 v[34:49], v[156:159], v[82:85], v[34:49]
	v_exp_f32_e32 v110, v110
	v_exp_f32_e32 v111, v111
	v_exp_f32_e32 v112, v112
	v_exp_f32_e32 v113, v113
	s_waitcnt lgkmcnt(6)
	v_mfma_f32_32x32x16_f16 v[18:33], v[152:155], v[86:89], v[18:33]
	v_exp_f32_e32 v2, v2
	v_exp_f32_e32 v3, v3
	v_exp_f32_e32 v4, v4
	v_exp_f32_e32 v5, v5
	s_waitcnt lgkmcnt(4)
	v_mfma_f32_32x32x16_f16 v[34:49], v[152:155], v[64:67], v[34:49]
	v_exp_f32_e32 v6, v6
	v_exp_f32_e32 v7, v7
	v_exp_f32_e32 v8, v8
	v_exp_f32_e32 v9, v9
	s_waitcnt lgkmcnt(2)
	v_mfma_f32_32x32x16_f16 v[18:33], v[148:151], v[68:71], v[18:33]
	v_exp_f32_e32 v10, v10
	v_exp_f32_e32 v11, v11
	v_exp_f32_e32 v12, v12
	v_exp_f32_e32 v13, v13
	s_waitcnt lgkmcnt(0)
; #define GAS __attribute__((address_space(1)))
; __device__ __forceinline__ int crow(int r, int hi) { return (r & 3) + 8 * (r >> 2) + 4 * hi; }
; #define SBAR() __builtin_amdgcn_sched_barrier(0)
; #define PKW(P, B) cvtpk_h(P[B], P[B + 1])
; #define PKW(P, B) cvtpk_h(P[B], P[B + 1])
; template <int THRL, bool FIXM> __device__ __forceinline__ bool attn_unit(const h16* Qrows, const h16* __restrict__ Kh, const h16* __restrict__ Vh, const int NT, h16* Yrows, const h16* BZrows, char* shm, const int tid, const float mfix, ...
;     ...
;   { float sacc = pB0[0] + pB0[1]; _Pragma("unroll") for (int r = 2; r < 16; ++r) sacc += pB0[r]; _Pragma("unroll") for (int r = 0; r < 16; ++r) sacc += pB1[r]; l_reg += sacc;
;     pw0 = (u32x4){PKW(pB0, 0), PKW(pB0, 2), PKW(pB0, 4), PKW(pB0, 6)}; pw1 = (u32x4){PKW(pB0, 8), PKW(pB0, 10), PKW(pB0, 12), PKW(pB0, 14)}; pw2 = (u32x4){PKW(pB1, 0), PKW(pB1, 2), PKW(pB1, 4), PKW(pB1, 6)}; pw3 = (u32x4){PKW(pB1, 8), PKW(pB1, 10), PKW(pB1, 12), PKW(pB1, 14)};
;     SBAR(); pv(o, vb0 + sl_cur, __builtin_bit_cast(s16x8, pw0), __builtin_bit_cast(s16x8, pw1), __builtin_bit_cast(s16x8, pw2), __builtin_bit_cast(s16x8, pw3)); }
;   h16x8 zg[4];
;   { const h16* Zw0 = BZrows + (long)(wid * QBLK) * ZP;
; #pragma unroll
;     for (int i = 0; i < 4; ++i) zg[i] = *(const GAS h16x8*)(Zw0 + (long)(i * 8 + (lane >> 3)) * ZP + (lane & 7) * 8); }
;     ...
;   { auto rr = __builtin_amdgcn_permlane32_swap(__float_as_uint(l_reg), __float_as_uint(l_reg), false, false); l_reg = __uint_as_float(rr[0]) + __uint_as_float(rr[1]); }
;   if (hi == 0) wsf[32 + r32] = l_reg; asm volatile("s_waitcnt lgkmcnt(0)" ::: "memory");
;   float rli[16];
; #pragma unroll
;   for (int r = 0; r < 16; ++r) rli[r] = __builtin_amdgcn_rcpf(wsf[32 + crow(r, hi)]);
;   h16* Yw = Yrows + (long)(wid * QBLK) * YP;
;   { h16* stg = (h16*)(shm + LDS_OST) + wid * 2048;
; #pragma unroll
;     for (int r = 0; r < 16; ++r) { const int orow = crow(r, hi);
; #pragma unroll
;       for (int d0 = 0; d0 < 2; ++d0) stg[orow * 64 + d0 * 32 + r32] = (h16)(o[d0][r] * rli[r]); }
	v_mfma_f32_32x32x16_f16 v[34:49], v[148:151], v[72:75], v[34:49]
	v_exp_f32_e32 v14, v14
	v_exp_f32_e32 v15, v15
	v_exp_f32_e32 v16, v16
	v_exp_f32_e32 v17, v17
	v_add_f32_e32 v51, v98, v99
	v_add_f32_e32 v51, v100, v51
	v_add_f32_e32 v51, v101, v51
	v_add_f32_e32 v51, v102, v51
	v_add_f32_e32 v51, v103, v51
	v_add_f32_e32 v51, v104, v51
	v_add_f32_e32 v51, v105, v51
	v_add_f32_e32 v51, v106, v51
	v_add_f32_e32 v51, v107, v51
	v_add_f32_e32 v51, v108, v51
	v_add_f32_e32 v51, v109, v51
	v_add_f32_e32 v51, v110, v51
	v_add_f32_e32 v51, v111, v51
	v_add_f32_e32 v51, v112, v51
	v_add_f32_e32 v82, v113, v51
	v_add_f32_e32 v83, v50, v0
	v_cvt_pk_f16_f32 v50, v98, v99
	v_cvt_pk_f16_f32 v51, v100, v101
	v_cvt_pk_f16_f32 v52, v102, v103
	v_cvt_pk_f16_f32 v53, v104, v105
	v_cvt_pk_f16_f32 v54, v106, v107
	v_cvt_pk_f16_f32 v55, v108, v109
	v_cvt_pk_f16_f32 v56, v110, v111
	v_cvt_pk_f16_f32 v57, v112, v113
	v_cvt_pk_f16_f32 v66, v2, v3
	v_cvt_pk_f16_f32 v67, v4, v5
	v_cvt_pk_f16_f32 v68, v6, v7
	v_cvt_pk_f16_f32 v69, v8, v9
	v_cvt_pk_f16_f32 v70, v10, v11
	v_cvt_pk_f16_f32 v71, v12, v13
	v_cvt_pk_f16_f32 v72, v14, v15
	v_cvt_pk_f16_f32 v73, v16, v17
	v_or3_b32 v0, v243, v232, v231
	s_add_i32 s12, s77, s17
	v_add_u32_e32 v0, s12, v0
	ds_read_b64_tr_b16 v[58:59],v0 offset:0
	ds_read_b64_tr_b16 v[60:61],v0 offset:512
	ds_read_b64_tr_b16 v[62:63],v0 offset:1024
	ds_read_b64_tr_b16 v[64:65],v0 offset:1536
	ds_read_b64_tr_b16 v[74:75],v0 offset:2048
	ds_read_b64_tr_b16 v[76:77],v0 offset:2560
	ds_read_b64_tr_b16 v[78:79],v0 offset:3072
	ds_read_b64_tr_b16 v[80:81],v0 offset:3584
	s_waitcnt lgkmcnt(0)
	s_nop 0
	v_mfma_f32_32x32x16_f16 v[18:33], v[50:53], v[58:61], v[18:33]
	ds_read_b64_tr_b16 v[58:59],v0 offset:4096
	ds_read_b64_tr_b16 v[60:61],v0 offset:4608
	v_mfma_f32_32x32x16_f16 v[18:33], v[54:57], v[62:65], v[18:33]
	ds_read_b64_tr_b16 v[62:63],v0 offset:5120
	ds_read_b64_tr_b16 v[64:65],v0 offset:5632
	v_mfma_f32_32x32x16_f16 v[18:33], v[66:69], v[74:77], v[18:33]
	ds_read_b64_tr_b16 v[74:75],v0 offset:6144
	ds_read_b64_tr_b16 v[76:77],v0 offset:6656
	v_mfma_f32_32x32x16_f16 v[18:33], v[70:73], v[78:81], v[18:33]
	ds_read_b64_tr_b16 v[78:79],v0 offset:7168
	ds_read_b64_tr_b16 v[80:81],v0 offset:7680
	s_waitcnt lgkmcnt(0)
	v_mfma_f32_32x32x16_f16 v[34:49], v[50:53], v[58:61], v[34:49]
	s_lshl_b64 s[12:13], s[24:25], 1
	s_add_u32 s12, s82, s12
	v_and_b32_e32 v0, 56, v131
	s_addc_u32 s13, s81, s13
	s_nop 0
	v_lshlrev_b32_e32 v0, 1, v0
	s_nop 0
	s_nop 0
	s_nop 0
	s_nop 0
	s_movk_i32 s12, 0x2000
	s_nop 0
	s_movk_i32 s12, 0x4000
	s_nop 0
	s_nop 0
	v_mfma_f32_32x32x16_f16 v[34:49], v[54:57], v[62:65], v[34:49]
	s_nop 0
	s_nop 0
	s_nop 0
	v_add_f32_e32 v2, v2, v82
	s_nop 0
	s_nop 0
	s_nop 0
	v_add_f32_e32 v2, v3, v2
	s_nop 0
	s_nop 0
	s_nop 0
	s_nop 0
	s_nop 0
	v_add_f32_e32 v2, v4, v2
	v_mfma_f32_32x32x16_f16 v[34:49], v[66:69], v[74:77], v[34:49]
	v_add_f32_e32 v2, v5, v2
	v_add_f32_e32 v2, v6, v2
	v_add_f32_e32 v2, v7, v2
	v_add_f32_e32 v2, v8, v2
	v_add_f32_e32 v2, v9, v2
	v_add_f32_e32 v2, v10, v2
	v_add_f32_e32 v2, v11, v2
	v_add_f32_e32 v2, v12, v2
	v_mfma_f32_32x32x16_f16 v[34:49], v[70:73], v[78:81], v[34:49]
	v_add_f32_e32 v2, v13, v2
	v_add_f32_e32 v2, v14, v2
	v_add_f32_e32 v2, v15, v2
	v_add_f32_e32 v2, v16, v2
	v_add_f32_e32 v2, v17, v2
	v_add_f32_e32 v2, v83, v2
	v_mov_b32_e32 v3, v2
	s_nop 1
	v_permlane32_swap_b32_e32 v2, v3
	v_cmp_gt_u32_e32 vcc, 32, v249
	s_and_saveexec_b64 s[12:13], vcc
	v_lshl_add_u32 v4, v250, 2, s14
	v_add_f32_e32 v2, v2, v3
	ds_write_b32 v4, v2 offset:49280
	s_or_b64 exec, exec, s[12:13]
	v_lshl_add_u32 v4, v248, 4, s14
	s_waitcnt lgkmcnt(0)
	v_add_u32_e32 v2, 0xc080, v4
	ds_read2_b32 v[2:3], v2 offset1:1
	s_lshl_b32 s12, s16, 12
	s_add_i32 s12, s41, s12
	v_lshlrev_b32_e32 v67, 1, v250
	s_lshl_b64 s[10:11], s[10:11], 11
	s_waitcnt lgkmcnt(0)
	v_rcp_f32_e32 v5, v2
	v_add_u32_e32 v2, 0xc088, v4
	v_rcp_f32_e32 v6, v3
	ds_read2_b32 v[2:3], v2 offset1:1
	s_add_u32 s10, s79, s10
	s_addc_u32 s11, s80, s11
	s_mov_b32 s51, 0x41000000
	s_waitcnt lgkmcnt(0)
	v_rcp_f32_e32 v7, v2
	v_add_u32_e32 v2, 0xc0a0, v4
	v_rcp_f32_e32 v8, v3
	ds_read2_b32 v[2:3], v2 offset1:1
	s_waitcnt lgkmcnt(0)
	v_rcp_f32_e32 v9, v2
	v_add_u32_e32 v2, 0xc0a8, v4
	v_rcp_f32_e32 v10, v3
	ds_read2_b32 v[2:3], v2 offset1:1
	s_waitcnt lgkmcnt(0)
	v_rcp_f32_e32 v11, v2
	v_add_u32_e32 v2, 0xc0c0, v4
	v_rcp_f32_e32 v12, v3
	ds_read2_b32 v[2:3], v2 offset1:1
	s_waitcnt lgkmcnt(0)
	v_rcp_f32_e32 v13, v2
	v_add_u32_e32 v2, 0xc0c8, v4
	v_rcp_f32_e32 v14, v3
	ds_read2_b32 v[2:3], v2 offset1:1
	s_waitcnt lgkmcnt(0)
	v_rcp_f32_e32 v15, v2
	v_add_u32_e32 v2, 0xc0e0, v4
	v_rcp_f32_e32 v16, v3
	ds_read2_b32 v[2:3], v2 offset1:1
	s_waitcnt lgkmcnt(0)
	v_rcp_f32_e32 v17, v2
	v_add_u32_e32 v2, 0xc0e8, v4
	v_fma_mixlo_f16 v4, v18, v5, 0
	v_lshlrev_b32_e32 v18, 1, v240
	v_add3_u32 v18, s12, v18, v67
	ds_write_b16 v18, v4 offset:51200
	v_fma_mixlo_f16 v4, v34, v5, 0
	ds_write_b16 v18, v4 offset:51264
	v_fma_mixlo_f16 v4, v19, v6, 0
	ds_write_b16 v18, v4 offset:51328
	v_fma_mixlo_f16 v4, v35, v6, 0
	ds_write_b16 v18, v4 offset:51392
	v_fma_mixlo_f16 v4, v20, v7, 0
	ds_write_b16 v18, v4 offset:51456
	v_fma_mixlo_f16 v4, v36, v7, 0
	ds_write_b16 v18, v4 offset:51520
	v_fma_mixlo_f16 v4, v21, v8, 0
	ds_write_b16 v18, v4 offset:51584
	v_fma_mixlo_f16 v4, v37, v8, 0
	ds_write_b16 v18, v4 offset:51648
	v_fma_mixlo_f16 v4, v22, v9, 0
	ds_write_b16 v18, v4 offset:52224
	v_fma_mixlo_f16 v4, v38, v9, 0
	ds_write_b16 v18, v4 offset:52288
	v_fma_mixlo_f16 v4, v23, v10, 0
	ds_write_b16 v18, v4 offset:52352
	v_fma_mixlo_f16 v4, v39, v10, 0
	ds_write_b16 v18, v4 offset:52416
	v_fma_mixlo_f16 v4, v24, v11, 0
	ds_write_b16 v18, v4 offset:52480
	v_fma_mixlo_f16 v4, v40, v11, 0
	ds_write_b16 v18, v4 offset:52544
	v_fma_mixlo_f16 v4, v25, v12, 0
	ds_write_b16 v18, v4 offset:52608
	v_fma_mixlo_f16 v4, v41, v12, 0
	ds_write_b16 v18, v4 offset:52672
	v_fma_mixlo_f16 v4, v26, v13, 0
	ds_write_b16 v18, v4 offset:53248
	v_fma_mixlo_f16 v4, v42, v13, 0
	ds_write_b16 v18, v4 offset:53312
	v_fma_mixlo_f16 v4, v27, v14, 0
	v_rcp_f32_e32 v66, v3
	ds_read2_b32 v[2:3], v2 offset1:1
	ds_write_b16 v18, v4 offset:53376
	v_fma_mixlo_f16 v4, v43, v14, 0
	ds_write_b16 v18, v4 offset:53440
	v_fma_mixlo_f16 v4, v28, v15, 0
	ds_write_b16 v18, v4 offset:53504
	v_fma_mixlo_f16 v4, v44, v15, 0
	ds_write_b16 v18, v4 offset:53568
	v_fma_mixlo_f16 v4, v29, v16, 0
	ds_write_b16 v18, v4 offset:53632
	v_fma_mixlo_f16 v4, v45, v16, 0
	s_waitcnt lgkmcnt(5)
; #define GAS __attribute__((address_space(1)))
; __device__ __forceinline__ float siluf(float x) { return x * __builtin_amdgcn_rcpf(1.f + __builtin_amdgcn_exp2f(-1.4426950408889634f * x)); }
; __device__ __forceinline__ unsigned cvtpk_h(float lo, float hi) { f32x2 v = {lo, hi}; h16x2 b = __builtin_convertvector(v, h16x2); return __builtin_bit_cast(unsigned, b); }
; __device__ __forceinline__ int crow(int r, int hi) { return (r & 3) + 8 * (r >> 2) + 4 * hi; }
; template <int THRL, bool FIXM> __device__ __forceinline__ bool attn_unit(const h16* Qrows, const h16* __restrict__ Kh, const h16* __restrict__ Vh, const int NT, h16* Yrows, const h16* BZrows, char* shm, const int tid, const float mfix, ...
;     ...
;   { h16* stg = (h16*)(shm + LDS_OST) + wid * 2048;
; #pragma unroll
;     for (int r = 0; r < 16; ++r) { const int orow = crow(r, hi);
; #pragma unroll
;       for (int d0 = 0; d0 < 2; ++d0) stg[orow * 64 + d0 * 32 + r32] = (h16)(o[d0][r] * rli[r]); }
;     asm volatile("s_waitcnt lgkmcnt(0)" ::: "memory");
; #pragma unroll
;     for (int i = 0; i < 4; ++i) { const int row = i * 8 + (lane >> 3), ch = lane & 7; const h16x8 v = *(const h16x8*)(stg + row * 64 + ch * 8); const h16x8 z = zg[i];
;       u32x4 w; w.x = cvtpk_h((float)v[0] * siluf((float)z[0]), (float)v[1] * siluf((float)z[1])); w.y = cvtpk_h((float)v[2] * siluf((float)z[2]), (float)v[3] * siluf((float)z[3]));
;       w.z = cvtpk_h((float)v[4] * siluf((float)z[4]), (float)v[5] * siluf((float)z[5])); w.w = cvtpk_h((float)v[6] * siluf((float)z[6]), (float)v[7] * siluf((float)z[7]));
;       *(GAS u32x4*)(Yw + (long)row * YP + ch * 8) = w; } }
	v_rcp_f32_e32 v2, v2
	ds_write_b16 v18, v4 offset:53696
	v_fma_mixlo_f16 v4, v30, v17, 0
	v_rcp_f32_e32 v3, v3
	ds_write_b16 v18, v4 offset:54272
	v_fma_mixlo_f16 v4, v46, v17, 0
	ds_write_b16 v18, v4 offset:54336
	v_fma_mixlo_f16 v4, v31, v66, 0
	ds_write_b16 v18, v4 offset:54400
	v_fma_mixlo_f16 v4, v47, v66, 0
	ds_write_b16 v18, v4 offset:54464
	v_fma_mixlo_f16 v4, v32, v2, 0
	v_fma_mixlo_f16 v2, v48, v2, 0
	ds_write_b16 v18, v2 offset:54592
	v_fma_mixlo_f16 v2, v33, v3, 0
	s_waitcnt vmcnt(3)
	v_cvt_f32_f16_e32 v8, v126
	ds_write_b16 v18, v2 offset:54656
	v_fma_mixlo_f16 v2, v49, v3, 0
	ds_write_b16 v18, v4 offset:54528
	ds_write_b16 v18, v2 offset:54720
	v_lshrrev_b32_e32 v10, 3, v249
	v_add_u32_e32 v11, s12, v0
	s_waitcnt lgkmcnt(0)
	v_lshl_add_u64 v[6:7], s[10:11], 0, v[0:1]
	v_lshl_add_u32 v0, v10, 7, v11
	ds_read_b128 v[2:5], v0 offset:51200
	v_mul_f32_e32 v0, 0xbfb8aa3b, v8
	v_exp_f32_e32 v0, v0
	v_cvt_f32_f16_sdwa v9, v126 dst_sel:DWORD dst_unused:UNUSED_PAD src0_sel:WORD_1
	s_mov_b64 s[10:11], 0
	s_waitcnt lgkmcnt(0)
	v_cvt_f32_f16_e32 v14, v2
	v_add_f32_e32 v0, 1.0, v0
	v_rcp_f32_e32 v12, v0
	v_mul_f32_e32 v0, 0xbfb8aa3b, v9
	v_exp_f32_e32 v0, v0
	v_cvt_f32_f16_sdwa v15, v2 dst_sel:DWORD dst_unused:UNUSED_PAD src0_sel:WORD_1
	v_add_f32_e32 v0, 1.0, v0
	v_rcp_f32_e32 v13, v0
	s_nop 0
	v_pk_mul_f32 v[8:9], v[12:13], v[8:9]
	s_nop 0
	v_pk_mul_f32 v[8:9], v[8:9], v[14:15]
	v_cvt_f32_f16_e32 v14, v3
	v_cvt_pk_f16_f32 v2, v8, v9
	v_cvt_f32_f16_e32 v8, v127
	v_cvt_f32_f16_sdwa v9, v127 dst_sel:DWORD dst_unused:UNUSED_PAD src0_sel:WORD_1
	v_cvt_f32_f16_sdwa v15, v3 dst_sel:DWORD dst_unused:UNUSED_PAD src0_sel:WORD_1
	v_mul_f32_e32 v0, 0xbfb8aa3b, v8
	v_exp_f32_e32 v0, v0
	s_nop 0
	v_add_f32_e32 v0, 1.0, v0
	v_rcp_f32_e32 v12, v0
	v_mul_f32_e32 v0, 0xbfb8aa3b, v9
	v_exp_f32_e32 v0, v0
	s_nop 0
	v_add_f32_e32 v0, 1.0, v0
	v_rcp_f32_e32 v13, v0
	s_nop 0
	v_pk_mul_f32 v[8:9], v[12:13], v[8:9]
	s_nop 0
	v_pk_mul_f32 v[8:9], v[8:9], v[14:15]
	v_cvt_f32_f16_e32 v14, v4
	v_cvt_pk_f16_f32 v3, v8, v9
	v_cvt_f32_f16_e32 v8, v128
	v_cvt_f32_f16_sdwa v9, v128 dst_sel:DWORD dst_unused:UNUSED_PAD src0_sel:WORD_1
	v_cvt_f32_f16_sdwa v15, v4 dst_sel:DWORD dst_unused:UNUSED_PAD src0_sel:WORD_1
	v_mul_f32_e32 v0, 0xbfb8aa3b, v8
	v_exp_f32_e32 v0, v0
	s_nop 0
	v_add_f32_e32 v0, 1.0, v0
	v_rcp_f32_e32 v12, v0
	v_mul_f32_e32 v0, 0xbfb8aa3b, v9
	v_exp_f32_e32 v0, v0
	s_nop 0
	v_add_f32_e32 v0, 1.0, v0
	v_rcp_f32_e32 v13, v0
	s_nop 0
	v_pk_mul_f32 v[8:9], v[12:13], v[8:9]
	s_nop 0
	v_pk_mul_f32 v[8:9], v[8:9], v[14:15]
	v_cvt_f32_f16_e32 v14, v5
	v_cvt_pk_f16_f32 v4, v8, v9
	v_cvt_f32_f16_e32 v8, v129
	v_cvt_f32_f16_sdwa v9, v129 dst_sel:DWORD dst_unused:UNUSED_PAD src0_sel:WORD_1
	v_cvt_f32_f16_sdwa v15, v5 dst_sel:DWORD dst_unused:UNUSED_PAD src0_sel:WORD_1
	v_mul_f32_e32 v0, 0xbfb8aa3b, v8
	v_exp_f32_e32 v0, v0
	s_nop 0
	v_add_f32_e32 v0, 1.0, v0
	v_rcp_f32_e32 v12, v0
	v_mul_f32_e32 v0, 0xbfb8aa3b, v9
	v_exp_f32_e32 v0, v0
	s_nop 0
	v_add_f32_e32 v0, 1.0, v0
	v_rcp_f32_e32 v13, v0
	v_lshlrev_b32_e32 v0, 11, v10
	v_pk_mul_f32 v[8:9], v[12:13], v[8:9]
	s_nop 0
	v_pk_mul_f32 v[8:9], v[8:9], v[14:15]
	s_nop 0
	v_cvt_pk_f16_f32 v5, v8, v9
	v_lshl_add_u64 v[8:9], v[6:7], 0, v[0:1]
	v_or_b32_e32 v0, 8, v10
	global_store_dwordx4 v[8:9], v[2:5], off offset:512
	s_waitcnt vmcnt(3)
	v_cvt_f32_f16_sdwa v9, v122 dst_sel:DWORD dst_unused:UNUSED_PAD src0_sel:WORD_1
	v_cvt_f32_f16_e32 v8, v122
	v_lshl_add_u32 v2, v0, 7, v11
	ds_read_b128 v[2:5], v2 offset:51200
	v_lshlrev_b32_e32 v0, 11, v0
	v_mul_f32_e32 v12, 0xbfb8aa3b, v8
	v_exp_f32_e32 v12, v12
	s_waitcnt lgkmcnt(0)
	v_cvt_f32_f16_e32 v14, v2
	v_cvt_f32_f16_sdwa v15, v2 dst_sel:DWORD dst_unused:UNUSED_PAD src0_sel:WORD_1
	v_mul_f32_e32 v2, 0xbfb8aa3b, v9
	v_exp_f32_e32 v2, v2
	v_add_f32_e32 v12, 1.0, v12
	v_rcp_f32_e32 v12, v12
	v_add_f32_e32 v2, 1.0, v2
	v_rcp_f32_e32 v13, v2
	s_nop 0
	v_pk_mul_f32 v[8:9], v[12:13], v[8:9]
	s_nop 0
	v_pk_mul_f32 v[8:9], v[8:9], v[14:15]
	v_cvt_f32_f16_e32 v14, v3
	v_cvt_pk_f16_f32 v2, v8, v9
	v_cvt_f32_f16_sdwa v9, v123 dst_sel:DWORD dst_unused:UNUSED_PAD src0_sel:WORD_1
	v_cvt_f32_f16_e32 v8, v123
	v_cvt_f32_f16_sdwa v15, v3 dst_sel:DWORD dst_unused:UNUSED_PAD src0_sel:WORD_1
	v_mul_f32_e32 v3, 0xbfb8aa3b, v9
	v_mul_f32_e32 v12, 0xbfb8aa3b, v8
	v_exp_f32_e32 v12, v12
	v_exp_f32_e32 v3, v3
	v_add_f32_e32 v12, 1.0, v12
	v_add_f32_e32 v3, 1.0, v3
	v_rcp_f32_e32 v12, v12
	v_rcp_f32_e32 v13, v3
	s_nop 0
	v_pk_mul_f32 v[8:9], v[12:13], v[8:9]
	s_nop 0
	v_pk_mul_f32 v[8:9], v[8:9], v[14:15]
	v_cvt_f32_f16_e32 v14, v4
	v_cvt_pk_f16_f32 v3, v8, v9
	v_cvt_f32_f16_sdwa v9, v124 dst_sel:DWORD dst_unused:UNUSED_PAD src0_sel:WORD_1
	v_cvt_f32_f16_e32 v8, v124
	v_cvt_f32_f16_sdwa v15, v4 dst_sel:DWORD dst_unused:UNUSED_PAD src0_sel:WORD_1
	v_mul_f32_e32 v4, 0xbfb8aa3b, v9
	v_mul_f32_e32 v12, 0xbfb8aa3b, v8
	v_exp_f32_e32 v12, v12
	v_exp_f32_e32 v4, v4
	v_add_f32_e32 v12, 1.0, v12
	v_add_f32_e32 v4, 1.0, v4
	v_rcp_f32_e32 v12, v12
	v_rcp_f32_e32 v13, v4
	s_nop 0
	v_pk_mul_f32 v[8:9], v[12:13], v[8:9]
	s_nop 0
	v_pk_mul_f32 v[8:9], v[8:9], v[14:15]
	v_cvt_f32_f16_e32 v14, v5
	v_cvt_pk_f16_f32 v4, v8, v9
	v_cvt_f32_f16_sdwa v9, v125 dst_sel:DWORD dst_unused:UNUSED_PAD src0_sel:WORD_1
	v_cvt_f32_f16_e32 v8, v125
	v_cvt_f32_f16_sdwa v15, v5 dst_sel:DWORD dst_unused:UNUSED_PAD src0_sel:WORD_1
	v_mul_f32_e32 v5, 0xbfb8aa3b, v9
	v_mul_f32_e32 v12, 0xbfb8aa3b, v8
	v_exp_f32_e32 v12, v12
	v_exp_f32_e32 v5, v5
	v_add_f32_e32 v12, 1.0, v12
	v_add_f32_e32 v5, 1.0, v5
	v_rcp_f32_e32 v12, v12
	v_rcp_f32_e32 v13, v5
	s_nop 0
	v_pk_mul_f32 v[8:9], v[12:13], v[8:9]
	s_nop 0
	v_pk_mul_f32 v[8:9], v[8:9], v[14:15]
	s_nop 0
	v_cvt_pk_f16_f32 v5, v8, v9
	v_lshl_add_u64 v[8:9], v[6:7], 0, v[0:1]
	v_or_b32_e32 v0, 16, v10
	global_store_dwordx4 v[8:9], v[2:5], off offset:512
	s_waitcnt vmcnt(3)
; #define GAS __attribute__((address_space(1)))
; __device__ __forceinline__ float siluf(float x) { return x * __builtin_amdgcn_rcpf(1.f + __builtin_amdgcn_exp2f(-1.4426950408889634f * x)); }
; __device__ __forceinline__ unsigned cvtpk_h(float lo, float hi) { f32x2 v = {lo, hi}; h16x2 b = __builtin_convertvector(v, h16x2); return __builtin_bit_cast(unsigned, b); }
; template <int THRL, bool FIXM> __device__ __forceinline__ bool attn_unit(const h16* Qrows, const h16* __restrict__ Kh, const h16* __restrict__ Vh, const int NT, h16* Yrows, const h16* BZrows, char* shm, const int tid, const float mfix, ...
;     ...
;     for (int i = 0; i < 4; ++i) { const int row = i * 8 + (lane >> 3), ch = lane & 7; const h16x8 v = *(const h16x8*)(stg + row * 64 + ch * 8); const h16x8 z = zg[i];
;       u32x4 w; w.x = cvtpk_h((float)v[0] * siluf((float)z[0]), (float)v[1] * siluf((float)z[1])); w.y = cvtpk_h((float)v[2] * siluf((float)z[2]), (float)v[3] * siluf((float)z[3]));
;       w.z = cvtpk_h((float)v[4] * siluf((float)z[4]), (float)v[5] * siluf((float)z[5])); w.w = cvtpk_h((float)v[6] * siluf((float)z[6]), (float)v[7] * siluf((float)z[7]));
;       *(GAS u32x4*)(Yw + (long)row * YP + ch * 8) = w; } }
;   asm volatile("s_waitcnt lgkmcnt(0)\n\ts_barrier" ::: "memory");
	v_cvt_f32_f16_sdwa v9, v118 dst_sel:DWORD dst_unused:UNUSED_PAD src0_sel:WORD_1
	v_cvt_f32_f16_e32 v8, v118
	v_lshl_add_u32 v2, v0, 7, v11
	ds_read_b128 v[2:5], v2 offset:51200
	v_lshlrev_b32_e32 v0, 11, v0
	v_mul_f32_e32 v12, 0xbfb8aa3b, v8
	v_exp_f32_e32 v12, v12
	s_waitcnt lgkmcnt(0)
	v_cvt_f32_f16_e32 v14, v2
	v_cvt_f32_f16_sdwa v15, v2 dst_sel:DWORD dst_unused:UNUSED_PAD src0_sel:WORD_1
	v_mul_f32_e32 v2, 0xbfb8aa3b, v9
	v_exp_f32_e32 v2, v2
	v_add_f32_e32 v12, 1.0, v12
	v_rcp_f32_e32 v12, v12
	v_add_f32_e32 v2, 1.0, v2
	v_rcp_f32_e32 v13, v2
	s_nop 0
	v_pk_mul_f32 v[8:9], v[12:13], v[8:9]
	s_nop 0
	v_pk_mul_f32 v[8:9], v[8:9], v[14:15]
	v_cvt_f32_f16_e32 v14, v3
	v_cvt_pk_f16_f32 v2, v8, v9
	v_cvt_f32_f16_sdwa v9, v119 dst_sel:DWORD dst_unused:UNUSED_PAD src0_sel:WORD_1
	v_cvt_f32_f16_e32 v8, v119
	v_cvt_f32_f16_sdwa v15, v3 dst_sel:DWORD dst_unused:UNUSED_PAD src0_sel:WORD_1
	v_mul_f32_e32 v3, 0xbfb8aa3b, v9
	v_mul_f32_e32 v12, 0xbfb8aa3b, v8
	v_exp_f32_e32 v12, v12
	v_exp_f32_e32 v3, v3
	v_add_f32_e32 v12, 1.0, v12
	v_add_f32_e32 v3, 1.0, v3
	v_rcp_f32_e32 v12, v12
	v_rcp_f32_e32 v13, v3
	s_nop 0
	v_pk_mul_f32 v[8:9], v[12:13], v[8:9]
	s_nop 0
	v_pk_mul_f32 v[8:9], v[8:9], v[14:15]
	v_cvt_f32_f16_e32 v14, v4
	v_cvt_pk_f16_f32 v3, v8, v9
	v_cvt_f32_f16_sdwa v9, v120 dst_sel:DWORD dst_unused:UNUSED_PAD src0_sel:WORD_1
	v_cvt_f32_f16_e32 v8, v120
	v_cvt_f32_f16_sdwa v15, v4 dst_sel:DWORD dst_unused:UNUSED_PAD src0_sel:WORD_1
	v_mul_f32_e32 v4, 0xbfb8aa3b, v9
	v_mul_f32_e32 v12, 0xbfb8aa3b, v8
	v_exp_f32_e32 v12, v12
	v_exp_f32_e32 v4, v4
	v_add_f32_e32 v12, 1.0, v12
	v_add_f32_e32 v4, 1.0, v4
	v_rcp_f32_e32 v12, v12
	v_rcp_f32_e32 v13, v4
	s_nop 0
	v_pk_mul_f32 v[8:9], v[12:13], v[8:9]
	s_nop 0
	v_pk_mul_f32 v[8:9], v[8:9], v[14:15]
	v_cvt_f32_f16_e32 v14, v5
	v_cvt_pk_f16_f32 v4, v8, v9
	v_cvt_f32_f16_sdwa v9, v121 dst_sel:DWORD dst_unused:UNUSED_PAD src0_sel:WORD_1
	v_cvt_f32_f16_e32 v8, v121
	v_cvt_f32_f16_sdwa v15, v5 dst_sel:DWORD dst_unused:UNUSED_PAD src0_sel:WORD_1
	v_mul_f32_e32 v5, 0xbfb8aa3b, v9
	v_mul_f32_e32 v12, 0xbfb8aa3b, v8
	v_exp_f32_e32 v12, v12
	v_exp_f32_e32 v5, v5
	v_add_f32_e32 v12, 1.0, v12
	v_add_f32_e32 v5, 1.0, v5
	v_rcp_f32_e32 v12, v12
	v_rcp_f32_e32 v13, v5
	s_nop 0
	v_pk_mul_f32 v[8:9], v[12:13], v[8:9]
	s_nop 0
	v_pk_mul_f32 v[8:9], v[8:9], v[14:15]
	s_nop 0
	v_cvt_pk_f16_f32 v5, v8, v9
	v_lshl_add_u64 v[8:9], v[6:7], 0, v[0:1]
	v_or_b32_e32 v0, 24, v10
	global_store_dwordx4 v[8:9], v[2:5], off offset:512
	s_waitcnt vmcnt(3)
	v_cvt_f32_f16_sdwa v9, v114 dst_sel:DWORD dst_unused:UNUSED_PAD src0_sel:WORD_1
	v_cvt_f32_f16_e32 v8, v114
	v_lshl_add_u32 v2, v0, 7, v11
	ds_read_b128 v[2:5], v2 offset:51200
	v_lshlrev_b32_e32 v0, 11, v0
	v_mul_f32_e32 v10, 0xbfb8aa3b, v8
	v_exp_f32_e32 v10, v10
	v_lshl_add_u64 v[6:7], v[6:7], 0, v[0:1]
	s_waitcnt lgkmcnt(0)
	v_cvt_f32_f16_e32 v12, v2
	v_cvt_f32_f16_sdwa v13, v2 dst_sel:DWORD dst_unused:UNUSED_PAD src0_sel:WORD_1
	v_mul_f32_e32 v2, 0xbfb8aa3b, v9
	v_exp_f32_e32 v2, v2
	v_add_f32_e32 v10, 1.0, v10
	v_rcp_f32_e32 v10, v10
	v_add_f32_e32 v2, 1.0, v2
	v_rcp_f32_e32 v11, v2
	s_nop 0
	v_pk_mul_f32 v[8:9], v[10:11], v[8:9]
	s_nop 0
	v_pk_mul_f32 v[8:9], v[8:9], v[12:13]
	v_cvt_f32_f16_e32 v12, v3
	v_cvt_pk_f16_f32 v2, v8, v9
	v_cvt_f32_f16_sdwa v9, v115 dst_sel:DWORD dst_unused:UNUSED_PAD src0_sel:WORD_1
	v_cvt_f32_f16_e32 v8, v115
	v_cvt_f32_f16_sdwa v13, v3 dst_sel:DWORD dst_unused:UNUSED_PAD src0_sel:WORD_1
	v_mul_f32_e32 v3, 0xbfb8aa3b, v9
	v_mul_f32_e32 v10, 0xbfb8aa3b, v8
	v_exp_f32_e32 v10, v10
	v_exp_f32_e32 v3, v3
	v_add_f32_e32 v10, 1.0, v10
	v_add_f32_e32 v3, 1.0, v3
	v_rcp_f32_e32 v10, v10
	v_rcp_f32_e32 v11, v3
	s_nop 0
	v_pk_mul_f32 v[8:9], v[10:11], v[8:9]
	s_nop 0
	v_pk_mul_f32 v[8:9], v[8:9], v[12:13]
	v_cvt_f32_f16_e32 v12, v4
	v_cvt_pk_f16_f32 v3, v8, v9
	v_cvt_f32_f16_sdwa v9, v116 dst_sel:DWORD dst_unused:UNUSED_PAD src0_sel:WORD_1
	v_cvt_f32_f16_e32 v8, v116
	v_cvt_f32_f16_sdwa v13, v4 dst_sel:DWORD dst_unused:UNUSED_PAD src0_sel:WORD_1
	v_mul_f32_e32 v4, 0xbfb8aa3b, v9
	v_mul_f32_e32 v10, 0xbfb8aa3b, v8
	v_exp_f32_e32 v10, v10
	v_exp_f32_e32 v4, v4
	v_add_f32_e32 v10, 1.0, v10
	v_add_f32_e32 v4, 1.0, v4
	v_rcp_f32_e32 v10, v10
	v_rcp_f32_e32 v11, v4
	s_nop 0
	v_pk_mul_f32 v[8:9], v[10:11], v[8:9]
	s_nop 0
	v_pk_mul_f32 v[8:9], v[8:9], v[12:13]
	v_cvt_f32_f16_e32 v12, v5
	v_cvt_pk_f16_f32 v4, v8, v9
	v_cvt_f32_f16_sdwa v9, v117 dst_sel:DWORD dst_unused:UNUSED_PAD src0_sel:WORD_1
	v_cvt_f32_f16_e32 v8, v117
	v_cvt_f32_f16_sdwa v13, v5 dst_sel:DWORD dst_unused:UNUSED_PAD src0_sel:WORD_1
	v_mul_f32_e32 v5, 0xbfb8aa3b, v9
	v_mul_f32_e32 v10, 0xbfb8aa3b, v8
	v_exp_f32_e32 v10, v10
	v_exp_f32_e32 v5, v5
	v_add_f32_e32 v10, 1.0, v10
	v_add_f32_e32 v5, 1.0, v5
	v_rcp_f32_e32 v10, v10
	v_rcp_f32_e32 v11, v5
	s_nop 0
	v_pk_mul_f32 v[8:9], v[10:11], v[8:9]
	s_nop 0
	v_pk_mul_f32 v[8:9], v[8:9], v[12:13]
	s_nop 0
	v_cvt_pk_f16_f32 v5, v8, v9
	global_store_dwordx4 v[6:7], v[2:5], off offset:512
	s_waitcnt lgkmcnt(0)
	s_barrier
